# non-temporal hint on the f32 residual loads and stores of the P4/P7 residual epilogues; on top of v138
# speedup vs baseline: 1.0031x; 1.0031x over previous
; #define EPI_FENCE() asm volatile("" ::: "memory")
; __device__ __forceinline__ u32x4 pack8(f32x4 a, f32x4 b) { u32x4 w; w.x = cvt_pk_bf16(a[0], a[1]); w.y = cvt_pk_bf16(a[2], a[3]); w.z = cvt_pk_bf16(b[0], b[1]); w.w = cvt_pk_bf16(b[2], b[3]); return w; }
; __device__ __forceinline__ float dot4(f32x4 a) { return (a[0] * a[0] + a[1] * a[1]) + (a[2] * a[2] + a[3] * a[3]); }
;   __device__ __forceinline__ void operator()(const AccT& acc, const pg8::Unit& u, int wr, int wc, int fr, int fq) const {
;     const int row0 = u.pm * 256 + wr * 64 + fr, col0 = u.pn * 256 + wc * 32 + 8 * fq;
; #pragma unroll
;     for (int ai = 0; ai < 2; ++ai)
; #pragma unroll
;       for (int m = 0; m < 4; ++m) { const int row = row0 + ai * 128 + m * 16; const size_t off = (size_t)row * DM + col0; float s = 0.f;
; #pragma unroll
;         for (int bj = 0; bj < 2; ++bj) { const int co = bj * 128;
;           const f32x4 v0 = *(const f32x4*)(base + off + co) + acc[ai][bj][m][0], v1 = *(const f32x4*)(base + off + co + 4) + acc[ai][bj][m][1];
;           *(f32x4*)(X + off + co) = v0; *(f32x4*)(X + off + co + 4) = v1; s += dot4(v0) + dot4(v1);
;           if (xb) { const f32x4 g0 = *(const f32x4*)(g + col0 + co), g1 = *(const f32x4*)(g + col0 + co + 4); *(u32x4*)(xb + off + co) = pack8(v0 * g0, v1 * g1); } }
;         s += __shfl_xor(s, 16); s += __shfl_xor(s, 32);
;         if (fq == 0) unsafeAtomicAdd(ss + row, s);
;         if (m & 1) EPI_FENCE(); }
;   }
.LBB0_516:
	v_lshl_add_u32 v149, s60, 8, v150
	v_lshl_or_b32 v252, s61, 8, v155
	v_lshlrev_b32_e32 v252, 2, v252
	v_lshl_add_u32 v148, v149, 13, v252
	v_lshlrev_b32_e32 v149, 2, v149
	global_load_dwordx4 v[144:147], v252, s[66:67]
	global_load_dwordx4 v[160:163], v252, s[66:67] offset:16
	global_load_dwordx4 v[164:167], v252, s[66:67] offset:512
	global_load_dwordx4 v[168:171], v252, s[66:67] offset:528
	v_xor_b32_e32 v254, 16, v159
	v_xor_b32_e32 v255, 32, v159
	v_lshlrev_b32_e32 v254, 2, v254
	v_lshlrev_b32_e32 v255, 2, v255
	global_load_dwordx4 v[172:175], v148, s[36:37] nt
	global_load_dwordx4 v[176:179], v148, s[36:37] offset:16 nt
	global_load_dwordx4 v[180:183], v148, s[36:37] offset:512 nt
	global_load_dwordx4 v[188:191], v148, s[36:37] offset:528 nt
	v_add_u32_e32 v253, 0x20000, v148
	global_load_dwordx4 v[194:197], v253, s[36:37] nt
	global_load_dwordx4 v[198:201], v253, s[36:37] offset:16 nt
	global_load_dwordx4 v[202:205], v253, s[36:37] offset:512 nt
	global_load_dwordx4 v[206:209], v253, s[36:37] offset:528 nt
	v_add_u32_e32 v253, 0x40000, v148
	global_load_dwordx4 v[210:213], v253, s[36:37] nt
	global_load_dwordx4 v[214:217], v253, s[36:37] offset:16 nt
	global_load_dwordx4 v[218:221], v253, s[36:37] offset:512 nt
	global_load_dwordx4 v[222:225], v253, s[36:37] offset:528 nt
	v_add_u32_e32 v253, 0x60000, v148
	global_load_dwordx4 v[234:237], v253, s[36:37] nt
	global_load_dwordx4 v[238:241], v253, s[36:37] offset:16 nt
	global_load_dwordx4 v[242:245], v253, s[36:37] offset:512 nt
	global_load_dwordx4 v[246:249], v253, s[36:37] offset:528 nt
	s_waitcnt vmcnt(12)
	v_pk_add_f32 v[120:121], v[120:121], v[172:173]
	v_pk_add_f32 v[122:123], v[122:123], v[174:175]
	v_pk_add_f32 v[124:125], v[124:125], v[176:177]
	v_pk_add_f32 v[126:127], v[126:127], v[178:179]
	v_pk_add_f32 v[116:117], v[116:117], v[180:181]
	v_pk_add_f32 v[118:119], v[118:119], v[182:183]
	v_pk_add_f32 v[112:113], v[112:113], v[188:189]
	v_pk_add_f32 v[114:115], v[114:115], v[190:191]
	global_store_dwordx4 v148, v[120:123], s[72:73] nt
	global_store_dwordx4 v148, v[124:127], s[72:73] offset:16 nt
	global_store_dwordx4 v148, v[116:119], s[72:73] offset:512 nt
	global_store_dwordx4 v148, v[112:115], s[72:73] offset:528 nt
	v_mul_f32_e32 v250, v120, v120
	v_mul_f32_e32 v251, v121, v121
	v_fmac_f32_e32 v250, v122, v122
	v_fmac_f32_e32 v251, v123, v123
	v_fmac_f32_e32 v250, v124, v124
	v_fmac_f32_e32 v251, v125, v125
	v_fmac_f32_e32 v250, v126, v126
	v_fmac_f32_e32 v251, v127, v127
	v_fmac_f32_e32 v250, v116, v116
	v_fmac_f32_e32 v251, v117, v117
	v_fmac_f32_e32 v250, v118, v118
	v_fmac_f32_e32 v251, v119, v119
	v_fmac_f32_e32 v250, v112, v112
	v_fmac_f32_e32 v251, v113, v113
	v_fmac_f32_e32 v250, v114, v114
	v_fmac_f32_e32 v251, v115, v115
	v_add_f32_e32 v250, v250, v251
	ds_bpermute_b32 v251, v254, v250
	v_pk_mul_f32 v[172:173], v[120:121], v[144:145]
	v_pk_mul_f32 v[174:175], v[122:123], v[146:147]
	v_pk_mul_f32 v[176:177], v[124:125], v[160:161]
	v_pk_mul_f32 v[178:179], v[126:127], v[162:163]
	v_pk_mul_f32 v[180:181], v[116:117], v[164:165]
	v_pk_mul_f32 v[182:183], v[118:119], v[166:167]
	v_pk_mul_f32 v[188:189], v[112:113], v[168:169]
	v_pk_mul_f32 v[190:191], v[114:115], v[170:171]
	v_cvt_pk_bf16_f32 v172, v172, v173
	v_cvt_pk_bf16_f32 v173, v174, v175
	v_cvt_pk_bf16_f32 v174, v176, v177
	v_cvt_pk_bf16_f32 v175, v178, v179
	v_cvt_pk_bf16_f32 v180, v180, v181
	v_cvt_pk_bf16_f32 v181, v182, v183
	v_cvt_pk_bf16_f32 v182, v188, v189
	v_cvt_pk_bf16_f32 v183, v190, v191
	v_lshrrev_b32_e32 v252, 1, v148
	global_store_dwordx4 v252, v[172:175], s[16:17]
	global_store_dwordx4 v252, v[180:183], s[16:17] offset:256
	s_waitcnt lgkmcnt(0)
	v_add_f32_e32 v250, v250, v251
	ds_bpermute_b32 v251, v255, v250
	s_nop 0
	v_add_u32_e32 v253, 0x100000, v148
	global_load_dwordx4 v[172:175], v253, s[36:37] nt
	global_load_dwordx4 v[176:179], v253, s[36:37] offset:16 nt
	global_load_dwordx4 v[180:183], v253, s[36:37] offset:512 nt
	global_load_dwordx4 v[188:191], v253, s[36:37] offset:528 nt
	s_waitcnt lgkmcnt(0)
	v_add_f32_e32 v250, v250, v251
	s_and_saveexec_b64 s[28:29], s[2:3]
	global_atomic_add_f32 v149, v250, s[18:19]
	s_mov_b64 exec, s[28:29]
	s_waitcnt vmcnt(19)
	v_pk_add_f32 v[108:109], v[108:109], v[194:195]
	v_pk_add_f32 v[110:111], v[110:111], v[196:197]
	v_pk_add_f32 v[104:105], v[104:105], v[198:199]
	v_pk_add_f32 v[106:107], v[106:107], v[200:201]
	v_pk_add_f32 v[100:101], v[100:101], v[202:203]
	v_pk_add_f32 v[102:103], v[102:103], v[204:205]
	v_pk_add_f32 v[96:97], v[96:97], v[206:207]
	v_pk_add_f32 v[98:99], v[98:99], v[208:209]
	v_add_u32_e32 v253, 0x20000, v148
	global_store_dwordx4 v253, v[108:111], s[72:73] nt
	global_store_dwordx4 v253, v[104:107], s[72:73] offset:16 nt
	global_store_dwordx4 v253, v[100:103], s[72:73] offset:512 nt
	global_store_dwordx4 v253, v[96:99], s[72:73] offset:528 nt
	v_mul_f32_e32 v250, v108, v108
	v_mul_f32_e32 v251, v109, v109
	v_fmac_f32_e32 v250, v110, v110
	v_fmac_f32_e32 v251, v111, v111
	v_fmac_f32_e32 v250, v104, v104
	v_fmac_f32_e32 v251, v105, v105
	v_fmac_f32_e32 v250, v106, v106
	v_fmac_f32_e32 v251, v107, v107
	v_fmac_f32_e32 v250, v100, v100
	v_fmac_f32_e32 v251, v101, v101
	v_fmac_f32_e32 v250, v102, v102
	v_fmac_f32_e32 v251, v103, v103
	v_fmac_f32_e32 v250, v96, v96
	v_fmac_f32_e32 v251, v97, v97
	v_fmac_f32_e32 v250, v98, v98
	v_fmac_f32_e32 v251, v99, v99
	v_add_f32_e32 v250, v250, v251
	ds_bpermute_b32 v251, v254, v250
	v_pk_mul_f32 v[194:195], v[108:109], v[144:145]
	v_pk_mul_f32 v[196:197], v[110:111], v[146:147]
	v_pk_mul_f32 v[198:199], v[104:105], v[160:161]
	v_pk_mul_f32 v[200:201], v[106:107], v[162:163]
	v_pk_mul_f32 v[202:203], v[100:101], v[164:165]
	v_pk_mul_f32 v[204:205], v[102:103], v[166:167]
	v_pk_mul_f32 v[206:207], v[96:97], v[168:169]
	v_pk_mul_f32 v[208:209], v[98:99], v[170:171]
	v_cvt_pk_bf16_f32 v194, v194, v195
	v_cvt_pk_bf16_f32 v195, v196, v197
	v_cvt_pk_bf16_f32 v196, v198, v199
	v_cvt_pk_bf16_f32 v197, v200, v201
	v_cvt_pk_bf16_f32 v202, v202, v203
	v_cvt_pk_bf16_f32 v203, v204, v205
	v_cvt_pk_bf16_f32 v204, v206, v207
	v_cvt_pk_bf16_f32 v205, v208, v209
	v_lshrrev_b32_e32 v252, 1, v253
	global_store_dwordx4 v252, v[194:197], s[16:17]
	global_store_dwordx4 v252, v[202:205], s[16:17] offset:256
	s_waitcnt lgkmcnt(0)
; #define EPI_FENCE() asm volatile("" ::: "memory")
; __device__ __forceinline__ u32x4 pack8(f32x4 a, f32x4 b) { u32x4 w; w.x = cvt_pk_bf16(a[0], a[1]); w.y = cvt_pk_bf16(a[2], a[3]); w.z = cvt_pk_bf16(b[0], b[1]); w.w = cvt_pk_bf16(b[2], b[3]); return w; }
; __device__ __forceinline__ float dot4(f32x4 a) { return (a[0] * a[0] + a[1] * a[1]) + (a[2] * a[2] + a[3] * a[3]); }
;   __device__ __forceinline__ void operator()(const AccT& acc, const pg8::Unit& u, int wr, int wc, int fr, int fq) const {
;     const int row0 = u.pm * 256 + wr * 64 + fr, col0 = u.pn * 256 + wc * 32 + 8 * fq;
; #pragma unroll
;     for (int ai = 0; ai < 2; ++ai)
; #pragma unroll
;       for (int m = 0; m < 4; ++m) { const int row = row0 + ai * 128 + m * 16; const size_t off = (size_t)row * DM + col0; float s = 0.f;
; #pragma unroll
;         for (int bj = 0; bj < 2; ++bj) { const int co = bj * 128;
;           const f32x4 v0 = *(const f32x4*)(base + off + co) + acc[ai][bj][m][0], v1 = *(const f32x4*)(base + off + co + 4) + acc[ai][bj][m][1];
;           *(f32x4*)(X + off + co) = v0; *(f32x4*)(X + off + co + 4) = v1; s += dot4(v0) + dot4(v1);
;           if (xb) { const f32x4 g0 = *(const f32x4*)(g + col0 + co), g1 = *(const f32x4*)(g + col0 + co + 4); *(u32x4*)(xb + off + co) = pack8(v0 * g0, v1 * g1); } }
;         s += __shfl_xor(s, 16); s += __shfl_xor(s, 32);
;         if (fq == 0) unsafeAtomicAdd(ss + row, s);
;         if (m & 1) EPI_FENCE(); }
;   }
	v_add_f32_e32 v250, v250, v251
	ds_bpermute_b32 v251, v255, v250
	v_add_u32_e32 v252, 0x40, v149
	s_nop 0
	v_add_u32_e32 v253, 0x120000, v148
	global_load_dwordx4 v[194:197], v253, s[36:37] nt
	global_load_dwordx4 v[198:201], v253, s[36:37] offset:16 nt
	global_load_dwordx4 v[202:205], v253, s[36:37] offset:512 nt
	global_load_dwordx4 v[206:209], v253, s[36:37] offset:528 nt
	s_waitcnt lgkmcnt(0)
	v_add_f32_e32 v250, v250, v251
	s_and_saveexec_b64 s[28:29], s[2:3]
	global_atomic_add_f32 v252, v250, s[18:19]
	s_mov_b64 exec, s[28:29]
	s_waitcnt vmcnt(26)
	v_pk_add_f32 v[92:93], v[92:93], v[210:211]
	v_pk_add_f32 v[94:95], v[94:95], v[212:213]
	v_pk_add_f32 v[88:89], v[88:89], v[214:215]
	v_pk_add_f32 v[90:91], v[90:91], v[216:217]
	v_pk_add_f32 v[84:85], v[84:85], v[218:219]
	v_pk_add_f32 v[86:87], v[86:87], v[220:221]
	v_pk_add_f32 v[80:81], v[80:81], v[222:223]
	v_pk_add_f32 v[82:83], v[82:83], v[224:225]
	v_add_u32_e32 v253, 0x40000, v148
	global_store_dwordx4 v253, v[92:95], s[72:73] nt
	global_store_dwordx4 v253, v[88:91], s[72:73] offset:16 nt
	global_store_dwordx4 v253, v[84:87], s[72:73] offset:512 nt
	global_store_dwordx4 v253, v[80:83], s[72:73] offset:528 nt
	v_mul_f32_e32 v250, v92, v92
	v_mul_f32_e32 v251, v93, v93
	v_fmac_f32_e32 v250, v94, v94
	v_fmac_f32_e32 v251, v95, v95
	v_fmac_f32_e32 v250, v88, v88
	v_fmac_f32_e32 v251, v89, v89
	v_fmac_f32_e32 v250, v90, v90
	v_fmac_f32_e32 v251, v91, v91
	v_fmac_f32_e32 v250, v84, v84
	v_fmac_f32_e32 v251, v85, v85
	v_fmac_f32_e32 v250, v86, v86
	v_fmac_f32_e32 v251, v87, v87
	v_fmac_f32_e32 v250, v80, v80
	v_fmac_f32_e32 v251, v81, v81
	v_fmac_f32_e32 v250, v82, v82
	v_fmac_f32_e32 v251, v83, v83
	v_add_f32_e32 v250, v250, v251
	ds_bpermute_b32 v251, v254, v250
	v_pk_mul_f32 v[210:211], v[92:93], v[144:145]
	v_pk_mul_f32 v[212:213], v[94:95], v[146:147]
	v_pk_mul_f32 v[214:215], v[88:89], v[160:161]
	v_pk_mul_f32 v[216:217], v[90:91], v[162:163]
	v_pk_mul_f32 v[218:219], v[84:85], v[164:165]
	v_pk_mul_f32 v[220:221], v[86:87], v[166:167]
	v_pk_mul_f32 v[222:223], v[80:81], v[168:169]
	v_pk_mul_f32 v[224:225], v[82:83], v[170:171]
	v_cvt_pk_bf16_f32 v210, v210, v211
	v_cvt_pk_bf16_f32 v211, v212, v213
	v_cvt_pk_bf16_f32 v212, v214, v215
	v_cvt_pk_bf16_f32 v213, v216, v217
	v_cvt_pk_bf16_f32 v218, v218, v219
	v_cvt_pk_bf16_f32 v219, v220, v221
	v_cvt_pk_bf16_f32 v220, v222, v223
	v_cvt_pk_bf16_f32 v221, v224, v225
	v_lshrrev_b32_e32 v252, 1, v253
	global_store_dwordx4 v252, v[210:213], s[16:17]
	global_store_dwordx4 v252, v[218:221], s[16:17] offset:256
	s_waitcnt lgkmcnt(0)
	v_add_f32_e32 v250, v250, v251
	ds_bpermute_b32 v251, v255, v250
	v_add_u32_e32 v252, 0x80, v149
	s_nop 0
	v_add_u32_e32 v253, 0x140000, v148
	global_load_dwordx4 v[210:213], v253, s[36:37] nt
	global_load_dwordx4 v[214:217], v253, s[36:37] offset:16 nt
	global_load_dwordx4 v[218:221], v253, s[36:37] offset:512 nt
	global_load_dwordx4 v[222:225], v253, s[36:37] offset:528 nt
	s_waitcnt lgkmcnt(0)
	v_add_f32_e32 v250, v250, v251
	s_and_saveexec_b64 s[28:29], s[2:3]
	global_atomic_add_f32 v252, v250, s[18:19]
	s_mov_b64 exec, s[28:29]
	s_waitcnt vmcnt(33)
	v_pk_add_f32 v[76:77], v[76:77], v[234:235]
	v_pk_add_f32 v[78:79], v[78:79], v[236:237]
	v_pk_add_f32 v[72:73], v[72:73], v[238:239]
	v_pk_add_f32 v[74:75], v[74:75], v[240:241]
	v_pk_add_f32 v[68:69], v[68:69], v[242:243]
	v_pk_add_f32 v[70:71], v[70:71], v[244:245]
	v_pk_add_f32 v[64:65], v[64:65], v[246:247]
	v_pk_add_f32 v[66:67], v[66:67], v[248:249]
	v_add_u32_e32 v253, 0x60000, v148
	global_store_dwordx4 v253, v[76:79], s[72:73] nt
	global_store_dwordx4 v253, v[72:75], s[72:73] offset:16 nt
	global_store_dwordx4 v253, v[68:71], s[72:73] offset:512 nt
	global_store_dwordx4 v253, v[64:67], s[72:73] offset:528 nt
	v_mul_f32_e32 v250, v76, v76
	v_mul_f32_e32 v251, v77, v77
	v_fmac_f32_e32 v250, v78, v78
	v_fmac_f32_e32 v251, v79, v79
	v_fmac_f32_e32 v250, v72, v72
	v_fmac_f32_e32 v251, v73, v73
	v_fmac_f32_e32 v250, v74, v74
	v_fmac_f32_e32 v251, v75, v75
	v_fmac_f32_e32 v250, v68, v68
	v_fmac_f32_e32 v251, v69, v69
	v_fmac_f32_e32 v250, v70, v70
	v_fmac_f32_e32 v251, v71, v71
	v_fmac_f32_e32 v250, v64, v64
	v_fmac_f32_e32 v251, v65, v65
	v_fmac_f32_e32 v250, v66, v66
	v_fmac_f32_e32 v251, v67, v67
	v_add_f32_e32 v250, v250, v251
	ds_bpermute_b32 v251, v254, v250
	v_pk_mul_f32 v[234:235], v[76:77], v[144:145]
	v_pk_mul_f32 v[236:237], v[78:79], v[146:147]
	v_pk_mul_f32 v[238:239], v[72:73], v[160:161]
	v_pk_mul_f32 v[240:241], v[74:75], v[162:163]
	v_pk_mul_f32 v[242:243], v[68:69], v[164:165]
	v_pk_mul_f32 v[244:245], v[70:71], v[166:167]
	v_pk_mul_f32 v[246:247], v[64:65], v[168:169]
	v_pk_mul_f32 v[248:249], v[66:67], v[170:171]
	v_cvt_pk_bf16_f32 v234, v234, v235
	v_cvt_pk_bf16_f32 v235, v236, v237
	v_cvt_pk_bf16_f32 v236, v238, v239
	v_cvt_pk_bf16_f32 v237, v240, v241
	v_cvt_pk_bf16_f32 v242, v242, v243
	v_cvt_pk_bf16_f32 v243, v244, v245
	v_cvt_pk_bf16_f32 v244, v246, v247
	v_cvt_pk_bf16_f32 v245, v248, v249
	v_lshrrev_b32_e32 v252, 1, v253
	global_store_dwordx4 v252, v[234:237], s[16:17]
	global_store_dwordx4 v252, v[242:245], s[16:17] offset:256
	s_waitcnt lgkmcnt(0)
	v_add_f32_e32 v250, v250, v251
	ds_bpermute_b32 v251, v255, v250
	v_add_u32_e32 v252, 0xc0, v149
	s_nop 0
	v_add_u32_e32 v253, 0x160000, v148
	global_load_dwordx4 v[234:237], v253, s[36:37] nt
	global_load_dwordx4 v[238:241], v253, s[36:37] offset:16 nt
	global_load_dwordx4 v[242:245], v253, s[36:37] offset:512 nt
	global_load_dwordx4 v[246:249], v253, s[36:37] offset:528 nt
	s_waitcnt lgkmcnt(0)
	v_add_f32_e32 v250, v250, v251
	s_and_saveexec_b64 s[28:29], s[2:3]
	global_atomic_add_f32 v252, v250, s[18:19]
	s_mov_b64 exec, s[28:29]
	s_waitcnt vmcnt(34)
; #define EPI_FENCE() asm volatile("" ::: "memory")
; __device__ __forceinline__ u32x4 pack8(f32x4 a, f32x4 b) { u32x4 w; w.x = cvt_pk_bf16(a[0], a[1]); w.y = cvt_pk_bf16(a[2], a[3]); w.z = cvt_pk_bf16(b[0], b[1]); w.w = cvt_pk_bf16(b[2], b[3]); return w; }
; __device__ __forceinline__ float dot4(f32x4 a) { return (a[0] * a[0] + a[1] * a[1]) + (a[2] * a[2] + a[3] * a[3]); }
;   __device__ __forceinline__ void operator()(const AccT& acc, const pg8::Unit& u, int wr, int wc, int fr, int fq) const {
;     const int row0 = u.pm * 256 + wr * 64 + fr, col0 = u.pn * 256 + wc * 32 + 8 * fq;
; #pragma unroll
;     for (int ai = 0; ai < 2; ++ai)
; #pragma unroll
;       for (int m = 0; m < 4; ++m) { const int row = row0 + ai * 128 + m * 16; const size_t off = (size_t)row * DM + col0; float s = 0.f;
; #pragma unroll
;         for (int bj = 0; bj < 2; ++bj) { const int co = bj * 128;
;           const f32x4 v0 = *(const f32x4*)(base + off + co) + acc[ai][bj][m][0], v1 = *(const f32x4*)(base + off + co + 4) + acc[ai][bj][m][1];
;           *(f32x4*)(X + off + co) = v0; *(f32x4*)(X + off + co + 4) = v1; s += dot4(v0) + dot4(v1);
;           if (xb) { const f32x4 g0 = *(const f32x4*)(g + col0 + co), g1 = *(const f32x4*)(g + col0 + co + 4); *(u32x4*)(xb + off + co) = pack8(v0 * g0, v1 * g1); } }
;         s += __shfl_xor(s, 16); s += __shfl_xor(s, 32);
;         if (fq == 0) unsafeAtomicAdd(ss + row, s);
;         if (m & 1) EPI_FENCE(); }
;   }
	v_pk_add_f32 v[60:61], v[60:61], v[172:173]
	v_pk_add_f32 v[62:63], v[62:63], v[174:175]
	v_pk_add_f32 v[56:57], v[56:57], v[176:177]
	v_pk_add_f32 v[58:59], v[58:59], v[178:179]
	v_pk_add_f32 v[52:53], v[52:53], v[180:181]
	v_pk_add_f32 v[54:55], v[54:55], v[182:183]
	v_pk_add_f32 v[48:49], v[48:49], v[188:189]
	v_pk_add_f32 v[50:51], v[50:51], v[190:191]
	v_add_u32_e32 v253, 0x100000, v148
	global_store_dwordx4 v253, v[60:63], s[72:73] nt
	global_store_dwordx4 v253, v[56:59], s[72:73] offset:16 nt
	global_store_dwordx4 v253, v[52:55], s[72:73] offset:512 nt
	global_store_dwordx4 v253, v[48:51], s[72:73] offset:528 nt
	v_mul_f32_e32 v250, v60, v60
	v_mul_f32_e32 v251, v61, v61
	v_fmac_f32_e32 v250, v62, v62
	v_fmac_f32_e32 v251, v63, v63
	v_fmac_f32_e32 v250, v56, v56
	v_fmac_f32_e32 v251, v57, v57
	v_fmac_f32_e32 v250, v58, v58
	v_fmac_f32_e32 v251, v59, v59
	v_fmac_f32_e32 v250, v52, v52
	v_fmac_f32_e32 v251, v53, v53
	v_fmac_f32_e32 v250, v54, v54
	v_fmac_f32_e32 v251, v55, v55
	v_fmac_f32_e32 v250, v48, v48
	v_fmac_f32_e32 v251, v49, v49
	v_fmac_f32_e32 v250, v50, v50
	v_fmac_f32_e32 v251, v51, v51
	v_add_f32_e32 v250, v250, v251
	ds_bpermute_b32 v251, v254, v250
	v_pk_mul_f32 v[172:173], v[60:61], v[144:145]
	v_pk_mul_f32 v[174:175], v[62:63], v[146:147]
	v_pk_mul_f32 v[176:177], v[56:57], v[160:161]
	v_pk_mul_f32 v[178:179], v[58:59], v[162:163]
	v_pk_mul_f32 v[180:181], v[52:53], v[164:165]
	v_pk_mul_f32 v[182:183], v[54:55], v[166:167]
	v_pk_mul_f32 v[188:189], v[48:49], v[168:169]
	v_pk_mul_f32 v[190:191], v[50:51], v[170:171]
	v_cvt_pk_bf16_f32 v172, v172, v173
	v_cvt_pk_bf16_f32 v173, v174, v175
	v_cvt_pk_bf16_f32 v174, v176, v177
	v_cvt_pk_bf16_f32 v175, v178, v179
	v_cvt_pk_bf16_f32 v180, v180, v181
	v_cvt_pk_bf16_f32 v181, v182, v183
	v_cvt_pk_bf16_f32 v182, v188, v189
	v_cvt_pk_bf16_f32 v183, v190, v191
	v_lshrrev_b32_e32 v252, 1, v253
	global_store_dwordx4 v252, v[172:175], s[16:17]
	global_store_dwordx4 v252, v[180:183], s[16:17] offset:256
	s_waitcnt lgkmcnt(0)
	v_add_f32_e32 v250, v250, v251
	ds_bpermute_b32 v251, v255, v250
	v_add_u32_e32 v252, 0x200, v149
	s_waitcnt lgkmcnt(0)
	v_add_f32_e32 v250, v250, v251
	s_and_saveexec_b64 s[28:29], s[2:3]
	global_atomic_add_f32 v252, v250, s[18:19]
	s_mov_b64 exec, s[28:29]
	s_waitcnt vmcnt(30)
	v_pk_add_f32 v[44:45], v[44:45], v[194:195]
	v_pk_add_f32 v[46:47], v[46:47], v[196:197]
	v_pk_add_f32 v[40:41], v[40:41], v[198:199]
	v_pk_add_f32 v[42:43], v[42:43], v[200:201]
	v_pk_add_f32 v[36:37], v[36:37], v[202:203]
	v_pk_add_f32 v[38:39], v[38:39], v[204:205]
	v_pk_add_f32 v[32:33], v[32:33], v[206:207]
	v_pk_add_f32 v[34:35], v[34:35], v[208:209]
	v_add_u32_e32 v253, 0x120000, v148
	global_store_dwordx4 v253, v[44:47], s[72:73] nt
	global_store_dwordx4 v253, v[40:43], s[72:73] offset:16 nt
	global_store_dwordx4 v253, v[36:39], s[72:73] offset:512 nt
	global_store_dwordx4 v253, v[32:35], s[72:73] offset:528 nt
	v_mul_f32_e32 v250, v44, v44
	v_mul_f32_e32 v251, v45, v45
	v_fmac_f32_e32 v250, v46, v46
	v_fmac_f32_e32 v251, v47, v47
	v_fmac_f32_e32 v250, v40, v40
	v_fmac_f32_e32 v251, v41, v41
	v_fmac_f32_e32 v250, v42, v42
	v_fmac_f32_e32 v251, v43, v43
	v_fmac_f32_e32 v250, v36, v36
	v_fmac_f32_e32 v251, v37, v37
	v_fmac_f32_e32 v250, v38, v38
	v_fmac_f32_e32 v251, v39, v39
	v_fmac_f32_e32 v250, v32, v32
	v_fmac_f32_e32 v251, v33, v33
	v_fmac_f32_e32 v250, v34, v34
	v_fmac_f32_e32 v251, v35, v35
	v_add_f32_e32 v250, v250, v251
	ds_bpermute_b32 v251, v254, v250
	v_pk_mul_f32 v[194:195], v[44:45], v[144:145]
	v_pk_mul_f32 v[196:197], v[46:47], v[146:147]
	v_pk_mul_f32 v[198:199], v[40:41], v[160:161]
	v_pk_mul_f32 v[200:201], v[42:43], v[162:163]
	v_pk_mul_f32 v[202:203], v[36:37], v[164:165]
	v_pk_mul_f32 v[204:205], v[38:39], v[166:167]
	v_pk_mul_f32 v[206:207], v[32:33], v[168:169]
	v_pk_mul_f32 v[208:209], v[34:35], v[170:171]
	v_cvt_pk_bf16_f32 v194, v194, v195
	v_cvt_pk_bf16_f32 v195, v196, v197
	v_cvt_pk_bf16_f32 v196, v198, v199
	v_cvt_pk_bf16_f32 v197, v200, v201
	v_cvt_pk_bf16_f32 v202, v202, v203
	v_cvt_pk_bf16_f32 v203, v204, v205
	v_cvt_pk_bf16_f32 v204, v206, v207
	v_cvt_pk_bf16_f32 v205, v208, v209
	v_lshrrev_b32_e32 v252, 1, v253
	global_store_dwordx4 v252, v[194:197], s[16:17]
	global_store_dwordx4 v252, v[202:205], s[16:17] offset:256
	s_waitcnt lgkmcnt(0)
	v_add_f32_e32 v250, v250, v251
	ds_bpermute_b32 v251, v255, v250
	v_add_u32_e32 v252, 0x240, v149
	s_waitcnt lgkmcnt(0)
	v_add_f32_e32 v250, v250, v251
	s_and_saveexec_b64 s[28:29], s[2:3]
	global_atomic_add_f32 v252, v250, s[18:19]
	s_mov_b64 exec, s[28:29]
	s_waitcnt vmcnt(26)
; #define EPI_FENCE() asm volatile("" ::: "memory")
; __device__ __forceinline__ u32x4 pack8(f32x4 a, f32x4 b) { u32x4 w; w.x = cvt_pk_bf16(a[0], a[1]); w.y = cvt_pk_bf16(a[2], a[3]); w.z = cvt_pk_bf16(b[0], b[1]); w.w = cvt_pk_bf16(b[2], b[3]); return w; }
; __device__ __forceinline__ float dot4(f32x4 a) { return (a[0] * a[0] + a[1] * a[1]) + (a[2] * a[2] + a[3] * a[3]); }
;   __device__ __forceinline__ void operator()(const AccT& acc, const pg8::Unit& u, int wr, int wc, int fr, int fq) const {
;     const int row0 = u.pm * 256 + wr * 64 + fr, col0 = u.pn * 256 + wc * 32 + 8 * fq;
; #pragma unroll
;     for (int ai = 0; ai < 2; ++ai)
; #pragma unroll
;       for (int m = 0; m < 4; ++m) { const int row = row0 + ai * 128 + m * 16; const size_t off = (size_t)row * DM + col0; float s = 0.f;
; #pragma unroll
;         for (int bj = 0; bj < 2; ++bj) { const int co = bj * 128;
;           const f32x4 v0 = *(const f32x4*)(base + off + co) + acc[ai][bj][m][0], v1 = *(const f32x4*)(base + off + co + 4) + acc[ai][bj][m][1];
;           *(f32x4*)(X + off + co) = v0; *(f32x4*)(X + off + co + 4) = v1; s += dot4(v0) + dot4(v1);
;           if (xb) { const f32x4 g0 = *(const f32x4*)(g + col0 + co), g1 = *(const f32x4*)(g + col0 + co + 4); *(u32x4*)(xb + off + co) = pack8(v0 * g0, v1 * g1); } }
;         s += __shfl_xor(s, 16); s += __shfl_xor(s, 32);
;         if (fq == 0) unsafeAtomicAdd(ss + row, s);
;         if (m & 1) EPI_FENCE(); }
;   }
	v_pk_add_f32 v[28:29], v[28:29], v[210:211]
	v_pk_add_f32 v[30:31], v[30:31], v[212:213]
	v_pk_add_f32 v[24:25], v[24:25], v[214:215]
	v_pk_add_f32 v[26:27], v[26:27], v[216:217]
	v_pk_add_f32 v[20:21], v[20:21], v[218:219]
	v_pk_add_f32 v[22:23], v[22:23], v[220:221]
	v_pk_add_f32 v[16:17], v[16:17], v[222:223]
	v_pk_add_f32 v[18:19], v[18:19], v[224:225]
	v_add_u32_e32 v253, 0x140000, v148
	global_store_dwordx4 v253, v[28:31], s[72:73] nt
	global_store_dwordx4 v253, v[24:27], s[72:73] offset:16 nt
	global_store_dwordx4 v253, v[20:23], s[72:73] offset:512 nt
	global_store_dwordx4 v253, v[16:19], s[72:73] offset:528 nt
	v_mul_f32_e32 v250, v28, v28
	v_mul_f32_e32 v251, v29, v29
	v_fmac_f32_e32 v250, v30, v30
	v_fmac_f32_e32 v251, v31, v31
	v_fmac_f32_e32 v250, v24, v24
	v_fmac_f32_e32 v251, v25, v25
	v_fmac_f32_e32 v250, v26, v26
	v_fmac_f32_e32 v251, v27, v27
	v_fmac_f32_e32 v250, v20, v20
	v_fmac_f32_e32 v251, v21, v21
	v_fmac_f32_e32 v250, v22, v22
	v_fmac_f32_e32 v251, v23, v23
	v_fmac_f32_e32 v250, v16, v16
	v_fmac_f32_e32 v251, v17, v17
	v_fmac_f32_e32 v250, v18, v18
	v_fmac_f32_e32 v251, v19, v19
	v_add_f32_e32 v250, v250, v251
	ds_bpermute_b32 v251, v254, v250
	v_pk_mul_f32 v[210:211], v[28:29], v[144:145]
	v_pk_mul_f32 v[212:213], v[30:31], v[146:147]
	v_pk_mul_f32 v[214:215], v[24:25], v[160:161]
	v_pk_mul_f32 v[216:217], v[26:27], v[162:163]
	v_pk_mul_f32 v[218:219], v[20:21], v[164:165]
	v_pk_mul_f32 v[220:221], v[22:23], v[166:167]
	v_pk_mul_f32 v[222:223], v[16:17], v[168:169]
	v_pk_mul_f32 v[224:225], v[18:19], v[170:171]
	v_cvt_pk_bf16_f32 v210, v210, v211
	v_cvt_pk_bf16_f32 v211, v212, v213
	v_cvt_pk_bf16_f32 v212, v214, v215
	v_cvt_pk_bf16_f32 v213, v216, v217
	v_cvt_pk_bf16_f32 v218, v218, v219
	v_cvt_pk_bf16_f32 v219, v220, v221
	v_cvt_pk_bf16_f32 v220, v222, v223
	v_cvt_pk_bf16_f32 v221, v224, v225
	v_lshrrev_b32_e32 v252, 1, v253
	global_store_dwordx4 v252, v[210:213], s[16:17]
	global_store_dwordx4 v252, v[218:221], s[16:17] offset:256
	s_waitcnt lgkmcnt(0)
	v_add_f32_e32 v250, v250, v251
	ds_bpermute_b32 v251, v255, v250
	v_add_u32_e32 v252, 0x280, v149
	s_waitcnt lgkmcnt(0)
	v_add_f32_e32 v250, v250, v251
	s_and_saveexec_b64 s[28:29], s[2:3]
	global_atomic_add_f32 v252, v250, s[18:19]
	s_mov_b64 exec, s[28:29]
	s_waitcnt vmcnt(22)
	v_pk_add_f32 v[12:13], v[12:13], v[234:235]
	v_pk_add_f32 v[14:15], v[14:15], v[236:237]
	v_pk_add_f32 v[8:9], v[8:9], v[238:239]
	v_pk_add_f32 v[10:11], v[10:11], v[240:241]
	v_pk_add_f32 v[4:5], v[4:5], v[242:243]
	v_pk_add_f32 v[6:7], v[6:7], v[244:245]
	v_pk_add_f32 v[0:1], v[0:1], v[246:247]
	v_pk_add_f32 v[2:3], v[2:3], v[248:249]
	v_add_u32_e32 v253, 0x160000, v148
	global_store_dwordx4 v253, v[12:15], s[72:73] nt
	global_store_dwordx4 v253, v[8:11], s[72:73] offset:16 nt
	global_store_dwordx4 v253, v[4:7], s[72:73] offset:512 nt
	global_store_dwordx4 v253, v[0:3], s[72:73] offset:528 nt
	v_mul_f32_e32 v250, v12, v12
	v_mul_f32_e32 v251, v13, v13
	v_fmac_f32_e32 v250, v14, v14
	v_fmac_f32_e32 v251, v15, v15
	v_fmac_f32_e32 v250, v8, v8
	v_fmac_f32_e32 v251, v9, v9
	v_fmac_f32_e32 v250, v10, v10
	v_fmac_f32_e32 v251, v11, v11
	v_fmac_f32_e32 v250, v4, v4
	v_fmac_f32_e32 v251, v5, v5
	v_fmac_f32_e32 v250, v6, v6
	v_fmac_f32_e32 v251, v7, v7
	v_fmac_f32_e32 v250, v0, v0
	v_fmac_f32_e32 v251, v1, v1
	v_fmac_f32_e32 v250, v2, v2
	v_fmac_f32_e32 v251, v3, v3
	v_add_f32_e32 v250, v250, v251
	ds_bpermute_b32 v251, v254, v250
	v_pk_mul_f32 v[234:235], v[12:13], v[144:145]
	v_pk_mul_f32 v[236:237], v[14:15], v[146:147]
	v_pk_mul_f32 v[238:239], v[8:9], v[160:161]
	v_pk_mul_f32 v[240:241], v[10:11], v[162:163]
	v_pk_mul_f32 v[242:243], v[4:5], v[164:165]
	v_pk_mul_f32 v[244:245], v[6:7], v[166:167]
	v_pk_mul_f32 v[246:247], v[0:1], v[168:169]
	v_pk_mul_f32 v[248:249], v[2:3], v[170:171]
	v_cvt_pk_bf16_f32 v234, v234, v235
	v_cvt_pk_bf16_f32 v235, v236, v237
	v_cvt_pk_bf16_f32 v236, v238, v239
	v_cvt_pk_bf16_f32 v237, v240, v241
	v_cvt_pk_bf16_f32 v242, v242, v243
	v_cvt_pk_bf16_f32 v243, v244, v245
	v_cvt_pk_bf16_f32 v244, v246, v247
	v_cvt_pk_bf16_f32 v245, v248, v249
	v_lshrrev_b32_e32 v252, 1, v253
	global_store_dwordx4 v252, v[234:237], s[16:17]
	global_store_dwordx4 v252, v[242:245], s[16:17] offset:256
	s_waitcnt lgkmcnt(0)
	v_add_f32_e32 v250, v250, v251
	ds_bpermute_b32 v251, v255, v250
	v_add_u32_e32 v252, 0x2c0, v149
	s_waitcnt lgkmcnt(0)
	v_add_f32_e32 v250, v250, v251
	s_and_saveexec_b64 s[28:29], s[2:3]
	global_atomic_add_f32 v252, v250, s[18:19]
	s_mov_b64 exec, s[28:29]
	s_branch .LBB0_502

; #define EPI_FENCE() asm volatile("" ::: "memory")
; __device__ __forceinline__ u32x4 pack8(f32x4 a, f32x4 b) { u32x4 w; w.x = cvt_pk_bf16(a[0], a[1]); w.y = cvt_pk_bf16(a[2], a[3]); w.z = cvt_pk_bf16(b[0], b[1]); w.w = cvt_pk_bf16(b[2], b[3]); return w; }
; __device__ __forceinline__ float dot4(f32x4 a) { return (a[0] * a[0] + a[1] * a[1]) + (a[2] * a[2] + a[3] * a[3]); }
;   __device__ __forceinline__ void operator()(const AccT& acc, const pg8::Unit& u, int wr, int wc, int fr, int fq) const {
;     const int row0 = u.pm * 256 + wr * 64 + fr, col0 = u.pn * 256 + wc * 32 + 8 * fq;
; #pragma unroll
;     for (int ai = 0; ai < 2; ++ai)
; #pragma unroll
;       for (int m = 0; m < 4; ++m) { const int row = row0 + ai * 128 + m * 16; const size_t off = (size_t)row * DM + col0; float s = 0.f;
; #pragma unroll
;         for (int bj = 0; bj < 2; ++bj) { const int co = bj * 128;
;           const f32x4 v0 = *(const f32x4*)(base + off + co) + acc[ai][bj][m][0], v1 = *(const f32x4*)(base + off + co + 4) + acc[ai][bj][m][1];
;           *(f32x4*)(X + off + co) = v0; *(f32x4*)(X + off + co + 4) = v1; s += dot4(v0) + dot4(v1);
;           if (xb) { const f32x4 g0 = *(const f32x4*)(g + col0 + co), g1 = *(const f32x4*)(g + col0 + co + 4); *(u32x4*)(xb + off + co) = pack8(v0 * g0, v1 * g1); } }
;         s += __shfl_xor(s, 16); s += __shfl_xor(s, 32);
;         if (fq == 0) unsafeAtomicAdd(ss + row, s);
;         if (m & 1) EPI_FENCE(); }
;   }
.LBB0_789:
	v_lshl_add_u32 v149, s56, 8, v150
	v_lshl_or_b32 v250, s57, 8, v152
	v_lshlrev_b32_e32 v250, 2, v250
	v_lshl_add_u32 v148, v149, 13, v250
	v_lshlrev_b32_e32 v149, 2, v149
	global_load_dwordx4 v[144:147], v250, s[26:27]
	global_load_dwordx4 v[158:161], v250, s[26:27] offset:16
	global_load_dwordx4 v[162:165], v250, s[26:27] offset:512
	global_load_dwordx4 v[166:169], v250, s[26:27] offset:528
	v_xor_b32_e32 v186, 16, v156
	v_xor_b32_e32 v252, 32, v156
	v_lshlrev_b32_e32 v186, 2, v186
	v_lshlrev_b32_e32 v252, 2, v252
	global_load_dwordx4 v[170:173], v148, s[72:73] nt
	global_load_dwordx4 v[174:177], v148, s[72:73] offset:16 nt
	global_load_dwordx4 v[178:181], v148, s[72:73] offset:512 nt
	global_load_dwordx4 v[182:185], v148, s[72:73] offset:528 nt
	v_add_u32_e32 v251, 0x20000, v148
	global_load_dwordx4 v[188:191], v251, s[72:73] nt
	global_load_dwordx4 v[194:197], v251, s[72:73] offset:16 nt
	global_load_dwordx4 v[198:201], v251, s[72:73] offset:512 nt
	global_load_dwordx4 v[202:205], v251, s[72:73] offset:528 nt
	v_add_u32_e32 v251, 0x40000, v148
	global_load_dwordx4 v[206:209], v251, s[72:73] nt
	global_load_dwordx4 v[210:213], v251, s[72:73] offset:16 nt
	global_load_dwordx4 v[214:217], v251, s[72:73] offset:512 nt
	global_load_dwordx4 v[218:221], v251, s[72:73] offset:528 nt
	v_add_u32_e32 v251, 0x60000, v148
	global_load_dwordx4 v[232:235], v251, s[72:73] nt
	global_load_dwordx4 v[236:239], v251, s[72:73] offset:16 nt
	global_load_dwordx4 v[240:243], v251, s[72:73] offset:512 nt
	global_load_dwordx4 v[244:247], v251, s[72:73] offset:528 nt
	s_waitcnt vmcnt(12)
	v_pk_add_f32 v[120:121], v[120:121], v[170:171]
	v_pk_add_f32 v[122:123], v[122:123], v[172:173]
	v_pk_add_f32 v[124:125], v[124:125], v[174:175]
	v_pk_add_f32 v[126:127], v[126:127], v[176:177]
	v_pk_add_f32 v[116:117], v[116:117], v[178:179]
	v_pk_add_f32 v[118:119], v[118:119], v[180:181]
	v_pk_add_f32 v[112:113], v[112:113], v[182:183]
	v_pk_add_f32 v[114:115], v[114:115], v[184:185]
	global_store_dwordx4 v148, v[120:123], s[72:73] nt
	global_store_dwordx4 v148, v[124:127], s[72:73] offset:16 nt
	global_store_dwordx4 v148, v[116:119], s[72:73] offset:512 nt
	global_store_dwordx4 v148, v[112:115], s[72:73] offset:528 nt
	v_mul_f32_e32 v248, v120, v120
	v_mul_f32_e32 v249, v121, v121
	v_fmac_f32_e32 v248, v122, v122
	v_fmac_f32_e32 v249, v123, v123
	v_fmac_f32_e32 v248, v124, v124
	v_fmac_f32_e32 v249, v125, v125
	v_fmac_f32_e32 v248, v126, v126
	v_fmac_f32_e32 v249, v127, v127
	v_fmac_f32_e32 v248, v116, v116
	v_fmac_f32_e32 v249, v117, v117
	v_fmac_f32_e32 v248, v118, v118
	v_fmac_f32_e32 v249, v119, v119
	v_fmac_f32_e32 v248, v112, v112
	v_fmac_f32_e32 v249, v113, v113
	v_fmac_f32_e32 v248, v114, v114
	v_fmac_f32_e32 v249, v115, v115
	v_add_f32_e32 v248, v248, v249
	ds_bpermute_b32 v249, v186, v248
	v_pk_mul_f32 v[170:171], v[120:121], v[144:145]
	v_pk_mul_f32 v[172:173], v[122:123], v[146:147]
	v_pk_mul_f32 v[174:175], v[124:125], v[158:159]
	v_pk_mul_f32 v[176:177], v[126:127], v[160:161]
	v_pk_mul_f32 v[178:179], v[116:117], v[162:163]
	v_pk_mul_f32 v[180:181], v[118:119], v[164:165]
	v_pk_mul_f32 v[182:183], v[112:113], v[166:167]
	v_pk_mul_f32 v[184:185], v[114:115], v[168:169]
	v_cvt_pk_bf16_f32 v170, v170, v171
	v_cvt_pk_bf16_f32 v171, v172, v173
	v_cvt_pk_bf16_f32 v172, v174, v175
	v_cvt_pk_bf16_f32 v173, v176, v177
	v_cvt_pk_bf16_f32 v178, v178, v179
	v_cvt_pk_bf16_f32 v179, v180, v181
	v_cvt_pk_bf16_f32 v180, v182, v183
	v_cvt_pk_bf16_f32 v181, v184, v185
	v_lshrrev_b32_e32 v250, 1, v148
	global_store_dwordx4 v250, v[170:173], s[16:17]
	global_store_dwordx4 v250, v[178:181], s[16:17] offset:256
	s_waitcnt lgkmcnt(0)
	v_add_f32_e32 v248, v248, v249
	ds_bpermute_b32 v249, v252, v248
	s_nop 0
	v_add_u32_e32 v251, 0x100000, v148
	global_load_dwordx4 v[170:173], v251, s[72:73] nt
	global_load_dwordx4 v[174:177], v251, s[72:73] offset:16 nt
	global_load_dwordx4 v[178:181], v251, s[72:73] offset:512 nt
	global_load_dwordx4 v[182:185], v251, s[72:73] offset:528 nt
	s_waitcnt lgkmcnt(0)
	v_add_f32_e32 v248, v248, v249
	s_and_saveexec_b64 s[24:25], s[2:3]
	global_atomic_add_f32 v149, v248, s[18:19]
	s_mov_b64 exec, s[24:25]
	s_waitcnt vmcnt(19)
	v_pk_add_f32 v[108:109], v[108:109], v[188:189]
	v_pk_add_f32 v[110:111], v[110:111], v[190:191]
	v_pk_add_f32 v[104:105], v[104:105], v[194:195]
	v_pk_add_f32 v[106:107], v[106:107], v[196:197]
	v_pk_add_f32 v[100:101], v[100:101], v[198:199]
	v_pk_add_f32 v[102:103], v[102:103], v[200:201]
	v_pk_add_f32 v[96:97], v[96:97], v[202:203]
	v_pk_add_f32 v[98:99], v[98:99], v[204:205]
	v_add_u32_e32 v251, 0x20000, v148
	global_store_dwordx4 v251, v[108:111], s[72:73] nt
	global_store_dwordx4 v251, v[104:107], s[72:73] offset:16 nt
	global_store_dwordx4 v251, v[100:103], s[72:73] offset:512 nt
	global_store_dwordx4 v251, v[96:99], s[72:73] offset:528 nt
	v_mul_f32_e32 v248, v108, v108
	v_mul_f32_e32 v249, v109, v109
	v_fmac_f32_e32 v248, v110, v110
	v_fmac_f32_e32 v249, v111, v111
	v_fmac_f32_e32 v248, v104, v104
	v_fmac_f32_e32 v249, v105, v105
	v_fmac_f32_e32 v248, v106, v106
	v_fmac_f32_e32 v249, v107, v107
	v_fmac_f32_e32 v248, v100, v100
	v_fmac_f32_e32 v249, v101, v101
	v_fmac_f32_e32 v248, v102, v102
	v_fmac_f32_e32 v249, v103, v103
	v_fmac_f32_e32 v248, v96, v96
	v_fmac_f32_e32 v249, v97, v97
	v_fmac_f32_e32 v248, v98, v98
	v_fmac_f32_e32 v249, v99, v99
	v_add_f32_e32 v248, v248, v249
	ds_bpermute_b32 v249, v186, v248
	v_pk_mul_f32 v[188:189], v[108:109], v[144:145]
	v_pk_mul_f32 v[190:191], v[110:111], v[146:147]
	v_pk_mul_f32 v[194:195], v[104:105], v[158:159]
	v_pk_mul_f32 v[196:197], v[106:107], v[160:161]
	v_pk_mul_f32 v[198:199], v[100:101], v[162:163]
	v_pk_mul_f32 v[200:201], v[102:103], v[164:165]
	v_pk_mul_f32 v[202:203], v[96:97], v[166:167]
	v_pk_mul_f32 v[204:205], v[98:99], v[168:169]
	v_cvt_pk_bf16_f32 v188, v188, v189
	v_cvt_pk_bf16_f32 v189, v190, v191
	v_cvt_pk_bf16_f32 v190, v194, v195
	v_cvt_pk_bf16_f32 v191, v196, v197
	v_cvt_pk_bf16_f32 v198, v198, v199
	v_cvt_pk_bf16_f32 v199, v200, v201
	v_cvt_pk_bf16_f32 v200, v202, v203
	v_cvt_pk_bf16_f32 v201, v204, v205
	v_lshrrev_b32_e32 v250, 1, v251
	global_store_dwordx4 v250, v[188:191], s[16:17]
	global_store_dwordx4 v250, v[198:201], s[16:17] offset:256
	s_waitcnt lgkmcnt(0)
; #define EPI_FENCE() asm volatile("" ::: "memory")
; __device__ __forceinline__ u32x4 pack8(f32x4 a, f32x4 b) { u32x4 w; w.x = cvt_pk_bf16(a[0], a[1]); w.y = cvt_pk_bf16(a[2], a[3]); w.z = cvt_pk_bf16(b[0], b[1]); w.w = cvt_pk_bf16(b[2], b[3]); return w; }
; __device__ __forceinline__ float dot4(f32x4 a) { return (a[0] * a[0] + a[1] * a[1]) + (a[2] * a[2] + a[3] * a[3]); }
;   __device__ __forceinline__ void operator()(const AccT& acc, const pg8::Unit& u, int wr, int wc, int fr, int fq) const {
;     const int row0 = u.pm * 256 + wr * 64 + fr, col0 = u.pn * 256 + wc * 32 + 8 * fq;
; #pragma unroll
;     for (int ai = 0; ai < 2; ++ai)
; #pragma unroll
;       for (int m = 0; m < 4; ++m) { const int row = row0 + ai * 128 + m * 16; const size_t off = (size_t)row * DM + col0; float s = 0.f;
; #pragma unroll
;         for (int bj = 0; bj < 2; ++bj) { const int co = bj * 128;
;           const f32x4 v0 = *(const f32x4*)(base + off + co) + acc[ai][bj][m][0], v1 = *(const f32x4*)(base + off + co + 4) + acc[ai][bj][m][1];
;           *(f32x4*)(X + off + co) = v0; *(f32x4*)(X + off + co + 4) = v1; s += dot4(v0) + dot4(v1);
;           if (xb) { const f32x4 g0 = *(const f32x4*)(g + col0 + co), g1 = *(const f32x4*)(g + col0 + co + 4); *(u32x4*)(xb + off + co) = pack8(v0 * g0, v1 * g1); } }
;         s += __shfl_xor(s, 16); s += __shfl_xor(s, 32);
;         if (fq == 0) unsafeAtomicAdd(ss + row, s);
;         if (m & 1) EPI_FENCE(); }
;   }
	v_add_f32_e32 v248, v248, v249
	ds_bpermute_b32 v249, v252, v248
	v_add_u32_e32 v250, 0x40, v149
	s_nop 0
	v_add_u32_e32 v251, 0x120000, v148
	global_load_dwordx4 v[188:191], v251, s[72:73] nt
	global_load_dwordx4 v[194:197], v251, s[72:73] offset:16 nt
	global_load_dwordx4 v[198:201], v251, s[72:73] offset:512 nt
	global_load_dwordx4 v[202:205], v251, s[72:73] offset:528 nt
	s_waitcnt lgkmcnt(0)
	v_add_f32_e32 v248, v248, v249
	s_and_saveexec_b64 s[24:25], s[2:3]
	global_atomic_add_f32 v250, v248, s[18:19]
	s_mov_b64 exec, s[24:25]
	s_waitcnt vmcnt(26)
	v_pk_add_f32 v[92:93], v[92:93], v[206:207]
	v_pk_add_f32 v[94:95], v[94:95], v[208:209]
	v_pk_add_f32 v[88:89], v[88:89], v[210:211]
	v_pk_add_f32 v[90:91], v[90:91], v[212:213]
	v_pk_add_f32 v[84:85], v[84:85], v[214:215]
	v_pk_add_f32 v[86:87], v[86:87], v[216:217]
	v_pk_add_f32 v[80:81], v[80:81], v[218:219]
	v_pk_add_f32 v[82:83], v[82:83], v[220:221]
	v_add_u32_e32 v251, 0x40000, v148
	global_store_dwordx4 v251, v[92:95], s[72:73] nt
	global_store_dwordx4 v251, v[88:91], s[72:73] offset:16 nt
	global_store_dwordx4 v251, v[84:87], s[72:73] offset:512 nt
	global_store_dwordx4 v251, v[80:83], s[72:73] offset:528 nt
	v_mul_f32_e32 v248, v92, v92
	v_mul_f32_e32 v249, v93, v93
	v_fmac_f32_e32 v248, v94, v94
	v_fmac_f32_e32 v249, v95, v95
	v_fmac_f32_e32 v248, v88, v88
	v_fmac_f32_e32 v249, v89, v89
	v_fmac_f32_e32 v248, v90, v90
	v_fmac_f32_e32 v249, v91, v91
	v_fmac_f32_e32 v248, v84, v84
	v_fmac_f32_e32 v249, v85, v85
	v_fmac_f32_e32 v248, v86, v86
	v_fmac_f32_e32 v249, v87, v87
	v_fmac_f32_e32 v248, v80, v80
	v_fmac_f32_e32 v249, v81, v81
	v_fmac_f32_e32 v248, v82, v82
	v_fmac_f32_e32 v249, v83, v83
	v_add_f32_e32 v248, v248, v249
	ds_bpermute_b32 v249, v186, v248
	v_pk_mul_f32 v[206:207], v[92:93], v[144:145]
	v_pk_mul_f32 v[208:209], v[94:95], v[146:147]
	v_pk_mul_f32 v[210:211], v[88:89], v[158:159]
	v_pk_mul_f32 v[212:213], v[90:91], v[160:161]
	v_pk_mul_f32 v[214:215], v[84:85], v[162:163]
	v_pk_mul_f32 v[216:217], v[86:87], v[164:165]
	v_pk_mul_f32 v[218:219], v[80:81], v[166:167]
	v_pk_mul_f32 v[220:221], v[82:83], v[168:169]
	v_cvt_pk_bf16_f32 v206, v206, v207
	v_cvt_pk_bf16_f32 v207, v208, v209
	v_cvt_pk_bf16_f32 v208, v210, v211
	v_cvt_pk_bf16_f32 v209, v212, v213
	v_cvt_pk_bf16_f32 v214, v214, v215
	v_cvt_pk_bf16_f32 v215, v216, v217
	v_cvt_pk_bf16_f32 v216, v218, v219
	v_cvt_pk_bf16_f32 v217, v220, v221
	v_lshrrev_b32_e32 v250, 1, v251
	global_store_dwordx4 v250, v[206:209], s[16:17]
	global_store_dwordx4 v250, v[214:217], s[16:17] offset:256
	s_waitcnt lgkmcnt(0)
	v_add_f32_e32 v248, v248, v249
	ds_bpermute_b32 v249, v252, v248
	v_add_u32_e32 v250, 0x80, v149
	s_nop 0
	v_add_u32_e32 v251, 0x140000, v148
	global_load_dwordx4 v[206:209], v251, s[72:73] nt
	global_load_dwordx4 v[210:213], v251, s[72:73] offset:16 nt
	global_load_dwordx4 v[214:217], v251, s[72:73] offset:512 nt
	global_load_dwordx4 v[218:221], v251, s[72:73] offset:528 nt
	s_waitcnt lgkmcnt(0)
	v_add_f32_e32 v248, v248, v249
	s_and_saveexec_b64 s[24:25], s[2:3]
	global_atomic_add_f32 v250, v248, s[18:19]
	s_mov_b64 exec, s[24:25]
	s_waitcnt vmcnt(33)
	v_pk_add_f32 v[76:77], v[76:77], v[232:233]
	v_pk_add_f32 v[78:79], v[78:79], v[234:235]
	v_pk_add_f32 v[72:73], v[72:73], v[236:237]
	v_pk_add_f32 v[74:75], v[74:75], v[238:239]
	v_pk_add_f32 v[68:69], v[68:69], v[240:241]
	v_pk_add_f32 v[70:71], v[70:71], v[242:243]
	v_pk_add_f32 v[64:65], v[64:65], v[244:245]
	v_pk_add_f32 v[66:67], v[66:67], v[246:247]
	v_add_u32_e32 v251, 0x60000, v148
	global_store_dwordx4 v251, v[76:79], s[72:73] nt
	global_store_dwordx4 v251, v[72:75], s[72:73] offset:16 nt
	global_store_dwordx4 v251, v[68:71], s[72:73] offset:512 nt
	global_store_dwordx4 v251, v[64:67], s[72:73] offset:528 nt
	v_mul_f32_e32 v248, v76, v76
	v_mul_f32_e32 v249, v77, v77
	v_fmac_f32_e32 v248, v78, v78
	v_fmac_f32_e32 v249, v79, v79
	v_fmac_f32_e32 v248, v72, v72
	v_fmac_f32_e32 v249, v73, v73
	v_fmac_f32_e32 v248, v74, v74
	v_fmac_f32_e32 v249, v75, v75
	v_fmac_f32_e32 v248, v68, v68
	v_fmac_f32_e32 v249, v69, v69
	v_fmac_f32_e32 v248, v70, v70
	v_fmac_f32_e32 v249, v71, v71
	v_fmac_f32_e32 v248, v64, v64
	v_fmac_f32_e32 v249, v65, v65
	v_fmac_f32_e32 v248, v66, v66
	v_fmac_f32_e32 v249, v67, v67
	v_add_f32_e32 v248, v248, v249
	ds_bpermute_b32 v249, v186, v248
	v_pk_mul_f32 v[232:233], v[76:77], v[144:145]
	v_pk_mul_f32 v[234:235], v[78:79], v[146:147]
	v_pk_mul_f32 v[236:237], v[72:73], v[158:159]
	v_pk_mul_f32 v[238:239], v[74:75], v[160:161]
	v_pk_mul_f32 v[240:241], v[68:69], v[162:163]
	v_pk_mul_f32 v[242:243], v[70:71], v[164:165]
	v_pk_mul_f32 v[244:245], v[64:65], v[166:167]
	v_pk_mul_f32 v[246:247], v[66:67], v[168:169]
	v_cvt_pk_bf16_f32 v232, v232, v233
	v_cvt_pk_bf16_f32 v233, v234, v235
	v_cvt_pk_bf16_f32 v234, v236, v237
	v_cvt_pk_bf16_f32 v235, v238, v239
	v_cvt_pk_bf16_f32 v240, v240, v241
	v_cvt_pk_bf16_f32 v241, v242, v243
	v_cvt_pk_bf16_f32 v242, v244, v245
	v_cvt_pk_bf16_f32 v243, v246, v247
	v_lshrrev_b32_e32 v250, 1, v251
	global_store_dwordx4 v250, v[232:235], s[16:17]
	global_store_dwordx4 v250, v[240:243], s[16:17] offset:256
	s_waitcnt lgkmcnt(0)
	v_add_f32_e32 v248, v248, v249
	ds_bpermute_b32 v249, v252, v248
	v_add_u32_e32 v250, 0xc0, v149
	s_nop 0
	v_add_u32_e32 v251, 0x160000, v148
	global_load_dwordx4 v[232:235], v251, s[72:73] nt
	global_load_dwordx4 v[236:239], v251, s[72:73] offset:16 nt
	global_load_dwordx4 v[240:243], v251, s[72:73] offset:512 nt
	global_load_dwordx4 v[244:247], v251, s[72:73] offset:528 nt
	s_waitcnt lgkmcnt(0)
	v_add_f32_e32 v248, v248, v249
	s_and_saveexec_b64 s[24:25], s[2:3]
	global_atomic_add_f32 v250, v248, s[18:19]
	s_mov_b64 exec, s[24:25]
	s_waitcnt vmcnt(34)
; #define EPI_FENCE() asm volatile("" ::: "memory")
; __device__ __forceinline__ u32x4 pack8(f32x4 a, f32x4 b) { u32x4 w; w.x = cvt_pk_bf16(a[0], a[1]); w.y = cvt_pk_bf16(a[2], a[3]); w.z = cvt_pk_bf16(b[0], b[1]); w.w = cvt_pk_bf16(b[2], b[3]); return w; }
; __device__ __forceinline__ float dot4(f32x4 a) { return (a[0] * a[0] + a[1] * a[1]) + (a[2] * a[2] + a[3] * a[3]); }
;   __device__ __forceinline__ void operator()(const AccT& acc, const pg8::Unit& u, int wr, int wc, int fr, int fq) const {
;     const int row0 = u.pm * 256 + wr * 64 + fr, col0 = u.pn * 256 + wc * 32 + 8 * fq;
; #pragma unroll
;     for (int ai = 0; ai < 2; ++ai)
; #pragma unroll
;       for (int m = 0; m < 4; ++m) { const int row = row0 + ai * 128 + m * 16; const size_t off = (size_t)row * DM + col0; float s = 0.f;
; #pragma unroll
;         for (int bj = 0; bj < 2; ++bj) { const int co = bj * 128;
;           const f32x4 v0 = *(const f32x4*)(base + off + co) + acc[ai][bj][m][0], v1 = *(const f32x4*)(base + off + co + 4) + acc[ai][bj][m][1];
;           *(f32x4*)(X + off + co) = v0; *(f32x4*)(X + off + co + 4) = v1; s += dot4(v0) + dot4(v1);
;           if (xb) { const f32x4 g0 = *(const f32x4*)(g + col0 + co), g1 = *(const f32x4*)(g + col0 + co + 4); *(u32x4*)(xb + off + co) = pack8(v0 * g0, v1 * g1); } }
;         s += __shfl_xor(s, 16); s += __shfl_xor(s, 32);
;         if (fq == 0) unsafeAtomicAdd(ss + row, s);
;         if (m & 1) EPI_FENCE(); }
;   }
	v_pk_add_f32 v[60:61], v[60:61], v[170:171]
	v_pk_add_f32 v[62:63], v[62:63], v[172:173]
	v_pk_add_f32 v[56:57], v[56:57], v[174:175]
	v_pk_add_f32 v[58:59], v[58:59], v[176:177]
	v_pk_add_f32 v[52:53], v[52:53], v[178:179]
	v_pk_add_f32 v[54:55], v[54:55], v[180:181]
	v_pk_add_f32 v[48:49], v[48:49], v[182:183]
	v_pk_add_f32 v[50:51], v[50:51], v[184:185]
	v_add_u32_e32 v251, 0x100000, v148
	global_store_dwordx4 v251, v[60:63], s[72:73] nt
	global_store_dwordx4 v251, v[56:59], s[72:73] offset:16 nt
	global_store_dwordx4 v251, v[52:55], s[72:73] offset:512 nt
	global_store_dwordx4 v251, v[48:51], s[72:73] offset:528 nt
	v_mul_f32_e32 v248, v60, v60
	v_mul_f32_e32 v249, v61, v61
	v_fmac_f32_e32 v248, v62, v62
	v_fmac_f32_e32 v249, v63, v63
	v_fmac_f32_e32 v248, v56, v56
	v_fmac_f32_e32 v249, v57, v57
	v_fmac_f32_e32 v248, v58, v58
	v_fmac_f32_e32 v249, v59, v59
	v_fmac_f32_e32 v248, v52, v52
	v_fmac_f32_e32 v249, v53, v53
	v_fmac_f32_e32 v248, v54, v54
	v_fmac_f32_e32 v249, v55, v55
	v_fmac_f32_e32 v248, v48, v48
	v_fmac_f32_e32 v249, v49, v49
	v_fmac_f32_e32 v248, v50, v50
	v_fmac_f32_e32 v249, v51, v51
	v_add_f32_e32 v248, v248, v249
	ds_bpermute_b32 v249, v186, v248
	v_pk_mul_f32 v[170:171], v[60:61], v[144:145]
	v_pk_mul_f32 v[172:173], v[62:63], v[146:147]
	v_pk_mul_f32 v[174:175], v[56:57], v[158:159]
	v_pk_mul_f32 v[176:177], v[58:59], v[160:161]
	v_pk_mul_f32 v[178:179], v[52:53], v[162:163]
	v_pk_mul_f32 v[180:181], v[54:55], v[164:165]
	v_pk_mul_f32 v[182:183], v[48:49], v[166:167]
	v_pk_mul_f32 v[184:185], v[50:51], v[168:169]
	v_cvt_pk_bf16_f32 v170, v170, v171
	v_cvt_pk_bf16_f32 v171, v172, v173
	v_cvt_pk_bf16_f32 v172, v174, v175
	v_cvt_pk_bf16_f32 v173, v176, v177
	v_cvt_pk_bf16_f32 v178, v178, v179
	v_cvt_pk_bf16_f32 v179, v180, v181
	v_cvt_pk_bf16_f32 v180, v182, v183
	v_cvt_pk_bf16_f32 v181, v184, v185
	v_lshrrev_b32_e32 v250, 1, v251
	global_store_dwordx4 v250, v[170:173], s[16:17]
	global_store_dwordx4 v250, v[178:181], s[16:17] offset:256
	s_waitcnt lgkmcnt(0)
	v_add_f32_e32 v248, v248, v249
	ds_bpermute_b32 v249, v252, v248
	v_add_u32_e32 v250, 0x200, v149
	s_waitcnt lgkmcnt(0)
	v_add_f32_e32 v248, v248, v249
	s_and_saveexec_b64 s[24:25], s[2:3]
	global_atomic_add_f32 v250, v248, s[18:19]
	s_mov_b64 exec, s[24:25]
	s_waitcnt vmcnt(30)
	v_pk_add_f32 v[44:45], v[44:45], v[188:189]
	v_pk_add_f32 v[46:47], v[46:47], v[190:191]
	v_pk_add_f32 v[40:41], v[40:41], v[194:195]
	v_pk_add_f32 v[42:43], v[42:43], v[196:197]
	v_pk_add_f32 v[36:37], v[36:37], v[198:199]
	v_pk_add_f32 v[38:39], v[38:39], v[200:201]
	v_pk_add_f32 v[32:33], v[32:33], v[202:203]
	v_pk_add_f32 v[34:35], v[34:35], v[204:205]
	v_add_u32_e32 v251, 0x120000, v148
	global_store_dwordx4 v251, v[44:47], s[72:73] nt
	global_store_dwordx4 v251, v[40:43], s[72:73] offset:16 nt
	global_store_dwordx4 v251, v[36:39], s[72:73] offset:512 nt
	global_store_dwordx4 v251, v[32:35], s[72:73] offset:528 nt
	v_mul_f32_e32 v248, v44, v44
	v_mul_f32_e32 v249, v45, v45
	v_fmac_f32_e32 v248, v46, v46
	v_fmac_f32_e32 v249, v47, v47
	v_fmac_f32_e32 v248, v40, v40
	v_fmac_f32_e32 v249, v41, v41
	v_fmac_f32_e32 v248, v42, v42
	v_fmac_f32_e32 v249, v43, v43
	v_fmac_f32_e32 v248, v36, v36
	v_fmac_f32_e32 v249, v37, v37
	v_fmac_f32_e32 v248, v38, v38
	v_fmac_f32_e32 v249, v39, v39
	v_fmac_f32_e32 v248, v32, v32
	v_fmac_f32_e32 v249, v33, v33
	v_fmac_f32_e32 v248, v34, v34
	v_fmac_f32_e32 v249, v35, v35
	v_add_f32_e32 v248, v248, v249
	ds_bpermute_b32 v249, v186, v248
	v_pk_mul_f32 v[188:189], v[44:45], v[144:145]
	v_pk_mul_f32 v[190:191], v[46:47], v[146:147]
	v_pk_mul_f32 v[194:195], v[40:41], v[158:159]
	v_pk_mul_f32 v[196:197], v[42:43], v[160:161]
	v_pk_mul_f32 v[198:199], v[36:37], v[162:163]
	v_pk_mul_f32 v[200:201], v[38:39], v[164:165]
	v_pk_mul_f32 v[202:203], v[32:33], v[166:167]
	v_pk_mul_f32 v[204:205], v[34:35], v[168:169]
	v_cvt_pk_bf16_f32 v188, v188, v189
	v_cvt_pk_bf16_f32 v189, v190, v191
	v_cvt_pk_bf16_f32 v190, v194, v195
	v_cvt_pk_bf16_f32 v191, v196, v197
	v_cvt_pk_bf16_f32 v198, v198, v199
	v_cvt_pk_bf16_f32 v199, v200, v201
	v_cvt_pk_bf16_f32 v200, v202, v203
	v_cvt_pk_bf16_f32 v201, v204, v205
	v_lshrrev_b32_e32 v250, 1, v251
	global_store_dwordx4 v250, v[188:191], s[16:17]
	global_store_dwordx4 v250, v[198:201], s[16:17] offset:256
	s_waitcnt lgkmcnt(0)
	v_add_f32_e32 v248, v248, v249
	ds_bpermute_b32 v249, v252, v248
	v_add_u32_e32 v250, 0x240, v149
	s_waitcnt lgkmcnt(0)
	v_add_f32_e32 v248, v248, v249
	s_and_saveexec_b64 s[24:25], s[2:3]
	global_atomic_add_f32 v250, v248, s[18:19]
	s_mov_b64 exec, s[24:25]
	s_waitcnt vmcnt(26)
; #define EPI_FENCE() asm volatile("" ::: "memory")
; __device__ __forceinline__ u32x4 pack8(f32x4 a, f32x4 b) { u32x4 w; w.x = cvt_pk_bf16(a[0], a[1]); w.y = cvt_pk_bf16(a[2], a[3]); w.z = cvt_pk_bf16(b[0], b[1]); w.w = cvt_pk_bf16(b[2], b[3]); return w; }
; __device__ __forceinline__ float dot4(f32x4 a) { return (a[0] * a[0] + a[1] * a[1]) + (a[2] * a[2] + a[3] * a[3]); }
;   __device__ __forceinline__ void operator()(const AccT& acc, const pg8::Unit& u, int wr, int wc, int fr, int fq) const {
;     const int row0 = u.pm * 256 + wr * 64 + fr, col0 = u.pn * 256 + wc * 32 + 8 * fq;
; #pragma unroll
;     for (int ai = 0; ai < 2; ++ai)
; #pragma unroll
;       for (int m = 0; m < 4; ++m) { const int row = row0 + ai * 128 + m * 16; const size_t off = (size_t)row * DM + col0; float s = 0.f;
; #pragma unroll
;         for (int bj = 0; bj < 2; ++bj) { const int co = bj * 128;
;           const f32x4 v0 = *(const f32x4*)(base + off + co) + acc[ai][bj][m][0], v1 = *(const f32x4*)(base + off + co + 4) + acc[ai][bj][m][1];
;           *(f32x4*)(X + off + co) = v0; *(f32x4*)(X + off + co + 4) = v1; s += dot4(v0) + dot4(v1);
;           if (xb) { const f32x4 g0 = *(const f32x4*)(g + col0 + co), g1 = *(const f32x4*)(g + col0 + co + 4); *(u32x4*)(xb + off + co) = pack8(v0 * g0, v1 * g1); } }
;         s += __shfl_xor(s, 16); s += __shfl_xor(s, 32);
;         if (fq == 0) unsafeAtomicAdd(ss + row, s);
;         if (m & 1) EPI_FENCE(); }
;   }
	v_pk_add_f32 v[28:29], v[28:29], v[206:207]
	v_pk_add_f32 v[30:31], v[30:31], v[208:209]
	v_pk_add_f32 v[24:25], v[24:25], v[210:211]
	v_pk_add_f32 v[26:27], v[26:27], v[212:213]
	v_pk_add_f32 v[20:21], v[20:21], v[214:215]
	v_pk_add_f32 v[22:23], v[22:23], v[216:217]
	v_pk_add_f32 v[16:17], v[16:17], v[218:219]
	v_pk_add_f32 v[18:19], v[18:19], v[220:221]
	v_add_u32_e32 v251, 0x140000, v148
	global_store_dwordx4 v251, v[28:31], s[72:73] nt
	global_store_dwordx4 v251, v[24:27], s[72:73] offset:16 nt
	global_store_dwordx4 v251, v[20:23], s[72:73] offset:512 nt
	global_store_dwordx4 v251, v[16:19], s[72:73] offset:528 nt
	v_mul_f32_e32 v248, v28, v28
	v_mul_f32_e32 v249, v29, v29
	v_fmac_f32_e32 v248, v30, v30
	v_fmac_f32_e32 v249, v31, v31
	v_fmac_f32_e32 v248, v24, v24
	v_fmac_f32_e32 v249, v25, v25
	v_fmac_f32_e32 v248, v26, v26
	v_fmac_f32_e32 v249, v27, v27
	v_fmac_f32_e32 v248, v20, v20
	v_fmac_f32_e32 v249, v21, v21
	v_fmac_f32_e32 v248, v22, v22
	v_fmac_f32_e32 v249, v23, v23
	v_fmac_f32_e32 v248, v16, v16
	v_fmac_f32_e32 v249, v17, v17
	v_fmac_f32_e32 v248, v18, v18
	v_fmac_f32_e32 v249, v19, v19
	v_add_f32_e32 v248, v248, v249
	ds_bpermute_b32 v249, v186, v248
	v_pk_mul_f32 v[206:207], v[28:29], v[144:145]
	v_pk_mul_f32 v[208:209], v[30:31], v[146:147]
	v_pk_mul_f32 v[210:211], v[24:25], v[158:159]
	v_pk_mul_f32 v[212:213], v[26:27], v[160:161]
	v_pk_mul_f32 v[214:215], v[20:21], v[162:163]
	v_pk_mul_f32 v[216:217], v[22:23], v[164:165]
	v_pk_mul_f32 v[218:219], v[16:17], v[166:167]
	v_pk_mul_f32 v[220:221], v[18:19], v[168:169]
	v_cvt_pk_bf16_f32 v206, v206, v207
	v_cvt_pk_bf16_f32 v207, v208, v209
	v_cvt_pk_bf16_f32 v208, v210, v211
	v_cvt_pk_bf16_f32 v209, v212, v213
	v_cvt_pk_bf16_f32 v214, v214, v215
	v_cvt_pk_bf16_f32 v215, v216, v217
	v_cvt_pk_bf16_f32 v216, v218, v219
	v_cvt_pk_bf16_f32 v217, v220, v221
	v_lshrrev_b32_e32 v250, 1, v251
	global_store_dwordx4 v250, v[206:209], s[16:17]
	global_store_dwordx4 v250, v[214:217], s[16:17] offset:256
	s_waitcnt lgkmcnt(0)
	v_add_f32_e32 v248, v248, v249
	ds_bpermute_b32 v249, v252, v248
	v_add_u32_e32 v250, 0x280, v149
	s_waitcnt lgkmcnt(0)
	v_add_f32_e32 v248, v248, v249
	s_and_saveexec_b64 s[24:25], s[2:3]
	global_atomic_add_f32 v250, v248, s[18:19]
	s_mov_b64 exec, s[24:25]
	s_waitcnt vmcnt(22)
	v_pk_add_f32 v[12:13], v[12:13], v[232:233]
	v_pk_add_f32 v[14:15], v[14:15], v[234:235]
	v_pk_add_f32 v[8:9], v[8:9], v[236:237]
	v_pk_add_f32 v[10:11], v[10:11], v[238:239]
	v_pk_add_f32 v[4:5], v[4:5], v[240:241]
	v_pk_add_f32 v[6:7], v[6:7], v[242:243]
	v_pk_add_f32 v[0:1], v[0:1], v[244:245]
	v_pk_add_f32 v[2:3], v[2:3], v[246:247]
	v_add_u32_e32 v251, 0x160000, v148
	global_store_dwordx4 v251, v[12:15], s[72:73] nt
	global_store_dwordx4 v251, v[8:11], s[72:73] offset:16 nt
	global_store_dwordx4 v251, v[4:7], s[72:73] offset:512 nt
	global_store_dwordx4 v251, v[0:3], s[72:73] offset:528 nt
	v_mul_f32_e32 v248, v12, v12
	v_mul_f32_e32 v249, v13, v13
	v_fmac_f32_e32 v248, v14, v14
	v_fmac_f32_e32 v249, v15, v15
	v_fmac_f32_e32 v248, v8, v8
	v_fmac_f32_e32 v249, v9, v9
	v_fmac_f32_e32 v248, v10, v10
	v_fmac_f32_e32 v249, v11, v11
	v_fmac_f32_e32 v248, v4, v4
	v_fmac_f32_e32 v249, v5, v5
	v_fmac_f32_e32 v248, v6, v6
	v_fmac_f32_e32 v249, v7, v7
	v_fmac_f32_e32 v248, v0, v0
	v_fmac_f32_e32 v249, v1, v1
	v_fmac_f32_e32 v248, v2, v2
	v_fmac_f32_e32 v249, v3, v3
	v_add_f32_e32 v248, v248, v249
	ds_bpermute_b32 v249, v186, v248
	v_pk_mul_f32 v[232:233], v[12:13], v[144:145]
	v_pk_mul_f32 v[234:235], v[14:15], v[146:147]
	v_pk_mul_f32 v[236:237], v[8:9], v[158:159]
	v_pk_mul_f32 v[238:239], v[10:11], v[160:161]
	v_pk_mul_f32 v[240:241], v[4:5], v[162:163]
	v_pk_mul_f32 v[242:243], v[6:7], v[164:165]
	v_pk_mul_f32 v[244:245], v[0:1], v[166:167]
	v_pk_mul_f32 v[246:247], v[2:3], v[168:169]
	v_cvt_pk_bf16_f32 v232, v232, v233
	v_cvt_pk_bf16_f32 v233, v234, v235
	v_cvt_pk_bf16_f32 v234, v236, v237
	v_cvt_pk_bf16_f32 v235, v238, v239
	v_cvt_pk_bf16_f32 v240, v240, v241
	v_cvt_pk_bf16_f32 v241, v242, v243
	v_cvt_pk_bf16_f32 v242, v244, v245
	v_cvt_pk_bf16_f32 v243, v246, v247
	v_lshrrev_b32_e32 v250, 1, v251
	global_store_dwordx4 v250, v[232:235], s[16:17]
	global_store_dwordx4 v250, v[240:243], s[16:17] offset:256
	s_waitcnt lgkmcnt(0)
	v_add_f32_e32 v248, v248, v249
	ds_bpermute_b32 v249, v252, v248
	v_add_u32_e32 v250, 0x2c0, v149
	s_waitcnt lgkmcnt(0)
	v_add_f32_e32 v248, v248, v249
	s_and_saveexec_b64 s[24:25], s[2:3]
	global_atomic_add_f32 v250, v248, s[18:19]
	s_mov_b64 exec, s[24:25]
	s_branch .LBB0_775
